# out-proj and FFN-down residual epilogues: first-half residual (x) loads of three row groups issued before the alignment barrier instead of behind two serial vector-load waits; vmcnt waits re-derived;
# speedup vs baseline: 1.0040x; 1.0040x over previous
; __device__ __forceinline__ unsigned pk2(float lo, float hi) { const f32x2 v = {lo, hi}; return __builtin_bit_cast(unsigned, __builtin_convertvector(v, bf16x2_t)); }
;     __device__ __forceinline__ void operator()(const f32x4 (&acc)[2][2][4][2], const Unit& un, int wr, int wc, int fr_, int fq_) const {
;     ...
;         f32x4 g0[2], g1[2], y0s[2], y1s[2];
; #pragma unroll
;         for (int bj = 0; bj < 2; ++bj) { const int col = cw + bj * 128; g0[bj] = *(const f32x4*)(gp + col); g1[bj] = *(const f32x4*)(gp + col + 4);
;             y0s[bj] = *(const f32x4*)(ng2 + col) * (*(const f32x4*)(sp2 + col) + 1.f); y1s[bj] = *(const f32x4*)(ng2 + col + 4) * (*(const f32x4*)(sp2 + col + 4) + 1.f); }
; #pragma unroll
;         for (int ai = 0; ai < 2; ++ai) {
;             f32x4 xa[4][2][2];
; #pragma unroll
;             for (int m = 0; m < 4; ++m)
; #pragma unroll
;                 for (int bj = 0; bj < 2; ++bj) { const float* sp = src + (size_t)(rbase + ai * 128 + m * 16 - radj) * D + cw + bj * 128; xa[m][bj][0] = *(const f32x4*)sp; xa[m][bj][1] = *(const f32x4*)(sp + 4); }
; #pragma unroll
;             for (int m = 0; m < 4; ++m)
; #pragma unroll
;                 for (int bj = 0; bj < 2; ++bj) { const int row = rbase + ai * 128 + m * 16, col = cw + bj * 128; const f32x4 v0 = acc[ai][bj][m][0], v1 = acc[ai][bj][m][1];
;                     float* dp = dst + (size_t)(row - radj) * D + col;
;                     const f32x4 x0 = xa[m][bj][0] + g0[bj] * v0, x1 = xa[m][bj][1] + g1[bj] * v1;
;                     *(f32x4*)dp = x0; *(f32x4*)(dp + 4) = x1;
;                     ssq[ai][m] += (x0.x * x0.x + x0.y * x0.y) + (x0.z * x0.z + x0.w * x0.w) + (x1.x * x1.x + x1.y * x1.y) + (x1.z * x1.z + x1.w * x1.w);
;                     const f32x4 y0 = x0 * y0s[bj], y1 = x1 * y1s[bj];
;                     u32x4 w; w.x = pk2(y0.x, y0.y); w.y = pk2(y0.z, y0.w); w.z = pk2(y1.x, y1.y); w.w = pk2(y1.z, y1.w); *(u32x4*)(xg + (size_t)row * D + col) = w; } }
.LBB0_1322:
	s_lshl_b32 s31, s40, 8
	s_add_i32 s31, s31, s64
	v_and_or_b32 v224, v211, 15, s31
	s_lshl_b32 s31, s38, 8
	s_or_b32 s31, s31, s65
	v_ashrrev_i32_e32 v116, 1, v211
	s_lshl_b64 s[40:41], s[46:47], 2
	v_and_b32_e32 v116, -8, v116
	s_add_u32 s46, s59, s40
	v_add_u32_e32 v248, s31, v116
	s_addc_u32 s47, s60, s41
	s_add_u32 s40, s61, s40
	v_ashrrev_i32_e32 v249, 31, v248
	s_addc_u32 s41, s62, s41
	v_lshlrev_b64 v[242:243], 2, v[248:249]
	v_lshl_add_u64 v[152:153], s[46:47], 0, v[242:243]
	v_lshl_add_u64 v[154:155], s[22:23], 0, v[242:243]
	v_lshl_add_u64 v[156:157], s[40:41], 0, v[242:243]
	global_load_dwordx4 v[128:131], v[152:153], off offset:16
	global_load_dwordx4 v[132:135], v[152:153], off
	global_load_dwordx4 v[116:119], v[154:155], off offset:16
	global_load_dwordx4 v[124:127], v[154:155], off
	global_load_dwordx4 v[144:147], v[156:157], off offset:16
	global_load_dwordx4 v[148:151], v[156:157], off
	v_subrev_u32_e32 v246, s29, v224
	v_ashrrev_i32_e32 v247, 31, v246
	v_lshl_add_u64 v[244:245], s[44:45], 0, v[242:243]
	v_lshlrev_b64 v[250:251], 13, v[246:247]
	v_lshl_add_u64 v[226:227], v[244:245], 0, v[250:251]
	global_load_dwordx4 v[200:203], v[226:227], off offset:16
	global_load_dwordx4 v[204:207], v[226:227], off
	global_load_dwordx4 v[192:195], v[226:227], off offset:528
	global_load_dwordx4 v[196:199], v[226:227], off offset:512
	v_or_b32_e32 v228, 16, v246
	v_ashrrev_i32_e32 v229, 31, v228
	v_lshlrev_b64 v[228:229], 13, v[228:229]
	v_lshl_add_u64 v[228:229], v[244:245], 0, v[228:229]
	global_load_dwordx4 v[184:187], v[228:229], off offset:16
	global_load_dwordx4 v[188:191], v[228:229], off
	global_load_dwordx4 v[176:179], v[228:229], off offset:528
	global_load_dwordx4 v[180:183], v[228:229], off offset:512
	v_or_b32_e32 v230, 32, v246
	v_ashrrev_i32_e32 v231, 31, v230
	v_lshlrev_b64 v[230:231], 13, v[230:231]
	v_lshl_add_u64 v[230:231], v[244:245], 0, v[230:231]
	global_load_dwordx4 v[168:171], v[230:231], off offset:16
	global_load_dwordx4 v[172:175], v[230:231], off
	global_load_dwordx4 v[160:163], v[230:231], off offset:528
	global_load_dwordx4 v[164:167], v[230:231], off offset:512
	s_and_b64 vcc, exec, s[26:27]
	s_cbranch_vccz .LBB0_1319
	s_barrier
.LBB0_1319:
	v_ashrrev_i32_e32 v225, 31, v224
	v_lshlrev_b64 v[212:213], 12, v[224:225]
	s_ashr_i32 s39, s38, 31
	v_cmp_gt_u32_e32 vcc, 16, v211
	s_lshl_b64 s[38:39], s[38:39], 4
	s_waitcnt vmcnt(12)
	v_pk_add_f32 v[150:151], v[150:151], 1.0 op_sel_hi:[1,0]
	v_pk_add_f32 v[148:149], v[148:149], 1.0 op_sel_hi:[1,0]
	v_pk_mul_f32 v[234:235], v[126:127], v[150:151]
	v_pk_mul_f32 v[236:237], v[124:125], v[148:149]
	v_pk_add_f32 v[124:125], v[146:147], 1.0 op_sel_hi:[1,0]
	v_pk_add_f32 v[126:127], v[144:145], 1.0 op_sel_hi:[1,0]
	v_pk_mul_f32 v[238:239], v[118:119], v[124:125]
	v_pk_mul_f32 v[240:241], v[116:117], v[126:127]
	global_load_dwordx4 v[116:119], v[152:153], off offset:528
	global_load_dwordx4 v[124:127], v[152:153], off offset:512
	global_load_dwordx4 v[144:147], v[154:155], off offset:528
	global_load_dwordx4 v[148:151], v[154:155], off offset:512
	s_nop 0
	global_load_dwordx4 v[152:155], v[156:157], off offset:528
	s_nop 0
	global_load_dwordx4 v[156:159], v[156:157], off offset:512
	s_waitcnt vmcnt(0)
	v_pk_add_f32 v[158:159], v[158:159], 1.0 op_sel_hi:[1,0]
	s_nop 0
	v_pk_mul_f32 v[226:227], v[150:151], v[158:159]
	v_pk_add_f32 v[150:151], v[152:153], 1.0 op_sel_hi:[1,0]
	v_pk_add_f32 v[156:157], v[156:157], 1.0 op_sel_hi:[1,0]
	v_pk_mul_f32 v[232:233], v[144:145], v[150:151]
	v_or_b32_e32 v144, 48, v246
	v_ashrrev_i32_e32 v145, 31, v144
	v_pk_mul_f32 v[228:229], v[148:149], v[156:157]
	v_pk_add_f32 v[148:149], v[154:155], 1.0 op_sel_hi:[1,0]
	v_lshlrev_b64 v[144:145], 13, v[144:145]
	v_pk_mul_f32 v[230:231], v[146:147], v[148:149]
	v_lshl_add_u64 v[148:149], v[244:245], 0, v[144:145]
	global_load_dwordx4 v[152:155], v[148:149], off offset:16
	global_load_dwordx4 v[156:159], v[148:149], off
	global_load_dwordx4 v[144:147], v[148:149], off offset:528
	s_nop 0
	global_load_dwordx4 v[148:151], v[148:149], off offset:512
	v_lshl_add_u64 v[250:251], s[42:43], 0, v[250:251]
	v_lshl_add_u64 v[250:251], v[250:251], 0, v[242:243]
	s_nop 0
	v_pk_fma_f32 v[136:137], v[136:137], v[128:129], v[200:201]
	s_nop 0
	v_pk_fma_f32 v[142:143], v[142:143], v[134:135], v[206:207]
	v_pk_fma_f32 v[140:141], v[140:141], v[132:133], v[204:205]
	v_mul_f32_e32 v201, v143, v143
	v_mul_f32_e32 v200, v141, v141
	v_fmac_f32_e32 v200, v140, v140
	v_fmac_f32_e32 v201, v142, v142
	v_add_f32_e32 v200, v200, v201
	v_mul_f32_e32 v201, v137, v137
	v_pk_fma_f32 v[138:139], v[138:139], v[130:131], v[202:203]
	v_fmac_f32_e32 v201, v136, v136
	v_add_f32_e32 v200, v200, v201
	v_mul_f32_e32 v201, v139, v139
	v_fmac_f32_e32 v201, v138, v138
	global_store_dwordx4 v[250:251], v[140:143], off
	global_store_dwordx4 v[250:251], v[136:139], off offset:16
	v_add_f32_e32 v202, v201, v200
	v_pk_mul_f32 v[140:141], v[236:237], v[140:141]
	v_pk_mul_f32 v[200:201], v[238:239], v[138:139]
	v_pk_mul_f32 v[138:139], v[240:241], v[136:137]
	v_pk_mul_f32 v[142:143], v[234:235], v[142:143]
	v_cvt_pk_bf16_f32 v136, v140, v141
	v_cvt_pk_bf16_f32 v138, v138, v139
	v_cvt_pk_bf16_f32 v139, v200, v201
	v_lshl_add_u64 v[140:141], s[20:21], 0, v[212:213]
	v_lshlrev_b64 v[200:201], 1, v[248:249]
	v_cvt_pk_bf16_f32 v137, v142, v143
	v_lshl_add_u64 v[140:141], v[140:141], 0, v[200:201]
	s_nop 0
	v_pk_fma_f32 v[122:123], v[122:123], v[126:127], v[198:199]
	v_pk_fma_f32 v[120:121], v[120:121], v[124:125], v[196:197]
	global_store_dwordx4 v[140:141], v[136:139], off
	v_pk_fma_f32 v[112:113], v[112:113], v[116:117], v[192:193]
; __device__ __forceinline__ unsigned pk2(float lo, float hi) { const f32x2 v = {lo, hi}; return __builtin_bit_cast(unsigned, __builtin_convertvector(v, bf16x2_t)); }
;     __device__ __forceinline__ void operator()(const f32x4 (&acc)[2][2][4][2], const Unit& un, int wr, int wc, int fr_, int fq_) const {
;     ...
; #pragma unroll
;             for (int m = 0; m < 4; ++m)
; #pragma unroll
;                 for (int bj = 0; bj < 2; ++bj) { const int row = rbase + ai * 128 + m * 16, col = cw + bj * 128; const f32x4 v0 = acc[ai][bj][m][0], v1 = acc[ai][bj][m][1];
;                     float* dp = dst + (size_t)(row - radj) * D + col;
;                     const f32x4 x0 = xa[m][bj][0] + g0[bj] * v0, x1 = xa[m][bj][1] + g1[bj] * v1;
;                     *(f32x4*)dp = x0; *(f32x4*)(dp + 4) = x1;
;                     ssq[ai][m] += (x0.x * x0.x + x0.y * x0.y) + (x0.z * x0.z + x0.w * x0.w) + (x1.x * x1.x + x1.y * x1.y) + (x1.z * x1.z + x1.w * x1.w);
;                     const f32x4 y0 = x0 * y0s[bj], y1 = x1 * y1s[bj];
;                     u32x4 w; w.x = pk2(y0.x, y0.y); w.y = pk2(y0.z, y0.w); w.z = pk2(y1.x, y1.y); w.w = pk2(y1.z, y1.w); *(u32x4*)(xg + (size_t)row * D + col) = w; } }
	v_pk_fma_f32 v[114:115], v[114:115], v[118:119], v[194:195]
	v_mul_f32_e32 v136, v121, v121
	v_mul_f32_e32 v137, v123, v123
	v_fmac_f32_e32 v136, v120, v120
	v_fmac_f32_e32 v137, v122, v122
	v_add_f32_e32 v136, v136, v137
	v_mul_f32_e32 v137, v113, v113
	v_fmac_f32_e32 v137, v112, v112
	v_add_f32_e32 v136, v136, v137
	v_mul_f32_e32 v137, v115, v115
	v_fmac_f32_e32 v137, v114, v114
	v_add_f32_e32 v136, v137, v136
	global_store_dwordx4 v[250:251], v[120:123], off offset:512
	global_store_dwordx4 v[250:251], v[112:115], off offset:528
	v_add_f32_e32 v194, v202, v136
	v_pk_mul_f32 v[122:123], v[226:227], v[122:123]
	v_pk_mul_f32 v[120:121], v[228:229], v[120:121]
	v_pk_mul_f32 v[136:137], v[230:231], v[114:115]
	v_pk_mul_f32 v[114:115], v[232:233], v[112:113]
	v_cvt_pk_bf16_f32 v112, v120, v121
	v_cvt_pk_bf16_f32 v113, v122, v123
	v_cvt_pk_bf16_f32 v114, v114, v115
	v_cvt_pk_bf16_f32 v115, v136, v137
	v_or_b32_e32 v192, 16, v224
	global_store_dwordx4 v[140:141], v[112:115], off offset:256
	v_ashrrev_i32_e32 v193, 31, v192
	v_lshlrev_b64 v[120:121], 12, v[192:193]
	v_subrev_u32_e32 v112, s29, v192
	v_ashrrev_i32_e32 v113, 31, v112
	v_lshlrev_b64 v[112:113], 13, v[112:113]
	v_lshl_add_u64 v[112:113], s[42:43], 0, v[112:113]
	s_nop 0
	v_pk_fma_f32 v[110:111], v[110:111], v[134:135], v[190:191]
	v_pk_fma_f32 v[108:109], v[108:109], v[132:133], v[188:189]
	v_pk_fma_f32 v[106:107], v[106:107], v[130:131], v[186:187]
	v_pk_fma_f32 v[104:105], v[104:105], v[128:129], v[184:185]
	v_lshl_add_u64 v[122:123], v[112:113], 0, v[242:243]
	v_pk_mul_f32 v[114:115], v[234:235], v[110:111]
	v_pk_mul_f32 v[112:113], v[236:237], v[108:109]
	v_pk_mul_f32 v[136:137], v[238:239], v[106:107]
	v_pk_mul_f32 v[138:139], v[240:241], v[104:105]
	v_lshl_add_u64 v[120:121], s[20:21], 0, v[120:121]
	v_cvt_pk_bf16_f32 v112, v112, v113
	v_cvt_pk_bf16_f32 v113, v114, v115
	v_cvt_pk_bf16_f32 v114, v138, v139
	v_cvt_pk_bf16_f32 v115, v136, v137
	v_lshl_add_u64 v[120:121], v[120:121], 0, v[200:201]
	s_nop 0
	v_pk_fma_f32 v[102:103], v[102:103], v[126:127], v[182:183]
	v_pk_fma_f32 v[100:101], v[100:101], v[124:125], v[180:181]
	v_pk_fma_f32 v[98:99], v[98:99], v[118:119], v[178:179]
	v_pk_fma_f32 v[96:97], v[96:97], v[116:117], v[176:177]
	global_store_dwordx4 v[122:123], v[108:111], off
	global_store_dwordx4 v[122:123], v[104:107], off offset:16
	global_store_dwordx4 v[120:121], v[112:115], off
	global_store_dwordx4 v[122:123], v[100:103], off offset:512
	global_store_dwordx4 v[122:123], v[96:99], off offset:528
	v_pk_mul_f32 v[114:115], v[226:227], v[102:103]
	v_pk_mul_f32 v[112:113], v[228:229], v[100:101]
	v_pk_mul_f32 v[122:123], v[230:231], v[98:99]
	v_pk_mul_f32 v[136:137], v[232:233], v[96:97]
	v_cvt_pk_bf16_f32 v112, v112, v113
	v_cvt_pk_bf16_f32 v113, v114, v115
	v_cvt_pk_bf16_f32 v114, v136, v137
	v_cvt_pk_bf16_f32 v115, v122, v123
	v_or_b32_e32 v176, 32, v224
	global_store_dwordx4 v[120:121], v[112:115], off offset:256
	v_ashrrev_i32_e32 v177, 31, v176
	v_lshlrev_b64 v[120:121], 12, v[176:177]
	v_subrev_u32_e32 v112, s29, v176
	v_ashrrev_i32_e32 v113, 31, v112
	v_lshlrev_b64 v[112:113], 13, v[112:113]
	v_lshl_add_u64 v[112:113], s[42:43], 0, v[112:113]
	s_nop 0
	v_pk_fma_f32 v[94:95], v[94:95], v[134:135], v[174:175]
	v_pk_fma_f32 v[92:93], v[92:93], v[132:133], v[172:173]
	v_pk_fma_f32 v[90:91], v[90:91], v[130:131], v[170:171]
	v_pk_fma_f32 v[88:89], v[88:89], v[128:129], v[168:169]
	v_lshl_add_u64 v[122:123], v[112:113], 0, v[242:243]
	v_pk_mul_f32 v[114:115], v[234:235], v[94:95]
	v_pk_mul_f32 v[112:113], v[236:237], v[92:93]
	v_pk_mul_f32 v[136:137], v[238:239], v[90:91]
	v_pk_mul_f32 v[138:139], v[240:241], v[88:89]
	v_lshl_add_u64 v[120:121], s[20:21], 0, v[120:121]
	v_cvt_pk_bf16_f32 v112, v112, v113
	v_cvt_pk_bf16_f32 v113, v114, v115
	v_cvt_pk_bf16_f32 v114, v138, v139
	v_cvt_pk_bf16_f32 v115, v136, v137
	v_lshl_add_u64 v[120:121], v[120:121], 0, v[200:201]
	s_nop 0
	v_pk_fma_f32 v[86:87], v[86:87], v[126:127], v[166:167]
	v_pk_fma_f32 v[84:85], v[84:85], v[124:125], v[164:165]
	v_pk_fma_f32 v[82:83], v[82:83], v[118:119], v[162:163]
	v_pk_fma_f32 v[80:81], v[80:81], v[116:117], v[160:161]
	global_store_dwordx4 v[122:123], v[92:95], off
	global_store_dwordx4 v[122:123], v[88:91], off offset:16
	global_store_dwordx4 v[120:121], v[112:115], off
	global_store_dwordx4 v[122:123], v[84:87], off offset:512
	global_store_dwordx4 v[122:123], v[80:83], off offset:528
	v_pk_mul_f32 v[114:115], v[226:227], v[86:87]
	v_pk_mul_f32 v[112:113], v[228:229], v[84:85]
	v_pk_mul_f32 v[122:123], v[230:231], v[82:83]
	v_pk_mul_f32 v[136:137], v[232:233], v[80:81]
	v_cvt_pk_bf16_f32 v112, v112, v113
	v_cvt_pk_bf16_f32 v113, v114, v115
	v_cvt_pk_bf16_f32 v114, v136, v137
	v_cvt_pk_bf16_f32 v115, v122, v123
	v_or_b32_e32 v160, 48, v224
	global_store_dwordx4 v[120:121], v[112:115], off offset:256
	v_ashrrev_i32_e32 v161, 31, v160
	v_lshlrev_b64 v[120:121], 12, v[160:161]
	v_subrev_u32_e32 v112, s29, v160
	v_ashrrev_i32_e32 v113, 31, v112
	v_lshlrev_b64 v[112:113], 13, v[112:113]
	v_lshl_add_u64 v[112:113], s[42:43], 0, v[112:113]
	s_waitcnt vmcnt(20)
	v_pk_fma_f32 v[78:79], v[78:79], v[134:135], v[158:159]
	v_pk_fma_f32 v[76:77], v[76:77], v[132:133], v[156:157]
	v_pk_fma_f32 v[74:75], v[74:75], v[130:131], v[154:155]
	v_pk_fma_f32 v[72:73], v[72:73], v[128:129], v[152:153]
	v_lshl_add_u64 v[122:123], v[112:113], 0, v[242:243]
	v_pk_mul_f32 v[114:115], v[234:235], v[78:79]
	v_pk_mul_f32 v[112:113], v[236:237], v[76:77]
	v_pk_mul_f32 v[136:137], v[238:239], v[74:75]
	v_pk_mul_f32 v[138:139], v[240:241], v[72:73]
	v_lshl_add_u64 v[120:121], s[20:21], 0, v[120:121]
	v_cvt_pk_bf16_f32 v112, v112, v113
	v_cvt_pk_bf16_f32 v113, v114, v115
	v_cvt_pk_bf16_f32 v114, v138, v139
	v_cvt_pk_bf16_f32 v115, v136, v137
	v_lshl_add_u64 v[120:121], v[120:121], 0, v[200:201]
	s_waitcnt vmcnt(18)
; __device__ __forceinline__ unsigned pk2(float lo, float hi) { const f32x2 v = {lo, hi}; return __builtin_bit_cast(unsigned, __builtin_convertvector(v, bf16x2_t)); }
;     __device__ __forceinline__ void operator()(const f32x4 (&acc)[2][2][4][2], const Unit& un, int wr, int wc, int fr_, int fq_) const {
;     ...
;         for (int ai = 0; ai < 2; ++ai) {
;             f32x4 xa[4][2][2];
; #pragma unroll
;             for (int m = 0; m < 4; ++m)
; #pragma unroll
;                 for (int bj = 0; bj < 2; ++bj) { const float* sp = src + (size_t)(rbase + ai * 128 + m * 16 - radj) * D + cw + bj * 128; xa[m][bj][0] = *(const f32x4*)sp; xa[m][bj][1] = *(const f32x4*)(sp + 4); }
; #pragma unroll
;             for (int m = 0; m < 4; ++m)
; #pragma unroll
;                 for (int bj = 0; bj < 2; ++bj) { const int row = rbase + ai * 128 + m * 16, col = cw + bj * 128; const f32x4 v0 = acc[ai][bj][m][0], v1 = acc[ai][bj][m][1];
;                     float* dp = dst + (size_t)(row - radj) * D + col;
;                     const f32x4 x0 = xa[m][bj][0] + g0[bj] * v0, x1 = xa[m][bj][1] + g1[bj] * v1;
;                     *(f32x4*)dp = x0; *(f32x4*)(dp + 4) = x1;
;                     ssq[ai][m] += (x0.x * x0.x + x0.y * x0.y) + (x0.z * x0.z + x0.w * x0.w) + (x1.x * x1.x + x1.y * x1.y) + (x1.z * x1.z + x1.w * x1.w);
;                     const f32x4 y0 = x0 * y0s[bj], y1 = x1 * y1s[bj];
;                     u32x4 w; w.x = pk2(y0.x, y0.y); w.y = pk2(y0.z, y0.w); w.z = pk2(y1.x, y1.y); w.w = pk2(y1.z, y1.w); *(u32x4*)(xg + (size_t)row * D + col) = w; } }
	v_pk_fma_f32 v[70:71], v[70:71], v[126:127], v[150:151]
	v_pk_fma_f32 v[68:69], v[68:69], v[124:125], v[148:149]
	v_pk_fma_f32 v[66:67], v[66:67], v[118:119], v[146:147]
	v_pk_fma_f32 v[64:65], v[64:65], v[116:117], v[144:145]
	global_store_dwordx4 v[122:123], v[76:79], off
	global_store_dwordx4 v[122:123], v[72:75], off offset:16
	global_store_dwordx4 v[120:121], v[112:115], off
	global_store_dwordx4 v[122:123], v[68:71], off offset:512
	global_store_dwordx4 v[122:123], v[64:67], off offset:528
	v_pk_mul_f32 v[114:115], v[226:227], v[70:71]
	v_pk_mul_f32 v[112:113], v[228:229], v[68:69]
	v_pk_mul_f32 v[122:123], v[230:231], v[66:67]
	v_pk_mul_f32 v[136:137], v[232:233], v[64:65]
	v_cvt_pk_bf16_f32 v112, v112, v113
	v_cvt_pk_bf16_f32 v113, v114, v115
	v_cvt_pk_bf16_f32 v114, v136, v137
	v_cvt_pk_bf16_f32 v115, v122, v123
	global_store_dwordx4 v[120:121], v[112:115], off offset:256
	v_add_u32_e32 v144, 0x80, v224
	v_subrev_u32_e32 v158, s29, v144
	v_add_u32_e32 v112, 0x80, v246
	v_ashrrev_i32_e32 v113, 31, v112
	v_lshlrev_b64 v[112:113], 13, v[112:113]
	v_lshl_add_u64 v[112:113], v[244:245], 0, v[112:113]
	global_load_dwordx4 v[146:149], v[112:113], off offset:16
	global_load_dwordx4 v[150:153], v[112:113], off
	global_load_dwordx4 v[154:157], v[112:113], off offset:528
	global_load_dwordx4 v[162:165], v[112:113], off offset:512
	v_add_u32_e32 v112, 0x90, v246
	v_ashrrev_i32_e32 v113, 31, v112
	v_lshlrev_b64 v[112:113], 13, v[112:113]
	v_lshl_add_u64 v[112:113], v[244:245], 0, v[112:113]
	global_load_dwordx4 v[166:169], v[112:113], off offset:16
	global_load_dwordx4 v[170:173], v[112:113], off
	global_load_dwordx4 v[178:181], v[112:113], off offset:528
	global_load_dwordx4 v[182:185], v[112:113], off offset:512
	v_add_u32_e32 v112, 0xa0, v246
	v_ashrrev_i32_e32 v113, 31, v112
	v_lshlrev_b64 v[112:113], 13, v[112:113]
	v_lshl_add_u64 v[112:113], v[244:245], 0, v[112:113]
	global_load_dwordx4 v[186:189], v[112:113], off offset:16
	global_load_dwordx4 v[196:199], v[112:113], off
	global_load_dwordx4 v[202:205], v[112:113], off offset:528
	global_load_dwordx4 v[248:251], v[112:113], off offset:512
	v_add_u32_e32 v112, 0xb0, v246
	v_ashrrev_i32_e32 v113, 31, v112
	v_lshlrev_b64 v[112:113], 13, v[112:113]
	v_lshl_add_u64 v[120:121], v[244:245], 0, v[112:113]
	global_load_dwordx4 v[136:139], v[120:121], off offset:16
	global_load_dwordx4 v[140:143], v[120:121], off
	global_load_dwordx4 v[112:115], v[120:121], off offset:528
	s_nop 0
	global_load_dwordx4 v[120:123], v[120:121], off offset:512
	v_ashrrev_i32_e32 v159, 31, v158
	v_ashrrev_i32_e32 v145, 31, v144
	v_lshlrev_b64 v[158:159], 13, v[158:159]
	v_lshlrev_b64 v[174:175], 12, v[144:145]
	v_lshl_add_u64 v[158:159], s[42:43], 0, v[158:159]
	v_lshl_add_u64 v[158:159], v[158:159], 0, v[242:243]
	s_waitcnt vmcnt(15)
	v_pk_fma_f32 v[58:59], v[58:59], v[130:131], v[148:149]
	s_waitcnt vmcnt(14)
	v_pk_fma_f32 v[62:63], v[62:63], v[134:135], v[152:153]
	v_pk_fma_f32 v[60:61], v[60:61], v[132:133], v[150:151]
	v_pk_fma_f32 v[56:57], v[56:57], v[128:129], v[146:147]
	v_pk_mul_f32 v[148:149], v[234:235], v[62:63]
	v_pk_mul_f32 v[146:147], v[236:237], v[60:61]
	v_pk_mul_f32 v[150:151], v[238:239], v[58:59]
	v_pk_mul_f32 v[152:153], v[240:241], v[56:57]
	v_cvt_pk_bf16_f32 v146, v146, v147
	v_cvt_pk_bf16_f32 v147, v148, v149
	v_cvt_pk_bf16_f32 v149, v150, v151
	v_lshl_add_u64 v[150:151], s[20:21], 0, v[174:175]
	v_cvt_pk_bf16_f32 v148, v152, v153
	v_lshl_add_u64 v[150:151], v[150:151], 0, v[200:201]
	s_waitcnt vmcnt(12)
	v_pk_fma_f32 v[54:55], v[54:55], v[126:127], v[164:165]
	v_pk_fma_f32 v[52:53], v[52:53], v[124:125], v[162:163]
	v_pk_fma_f32 v[50:51], v[50:51], v[118:119], v[156:157]
	v_pk_fma_f32 v[48:49], v[48:49], v[116:117], v[154:155]
	global_store_dwordx4 v[158:159], v[60:63], off
	global_store_dwordx4 v[158:159], v[56:59], off offset:16
	global_store_dwordx4 v[150:151], v[146:149], off
	v_pk_mul_f32 v[152:153], v[230:231], v[50:51]
	v_pk_mul_f32 v[154:155], v[232:233], v[48:49]
	v_pk_mul_f32 v[148:149], v[226:227], v[54:55]
	v_pk_mul_f32 v[146:147], v[228:229], v[52:53]
	global_store_dwordx4 v[158:159], v[52:55], off offset:512
	global_store_dwordx4 v[158:159], v[48:51], off offset:528
	v_cvt_pk_bf16_f32 v146, v146, v147
	v_cvt_pk_bf16_f32 v147, v148, v149
	v_cvt_pk_bf16_f32 v148, v154, v155
	v_cvt_pk_bf16_f32 v149, v152, v153
	global_store_dwordx4 v[150:151], v[146:149], off offset:256
	s_waitcnt vmcnt(16)
	v_pk_fma_f32 v[46:47], v[46:47], v[134:135], v[172:173]
	v_pk_fma_f32 v[44:45], v[44:45], v[132:133], v[170:171]
	v_add_u32_e32 v146, 0x90, v224
	v_subrev_u32_e32 v148, s29, v146
	v_ashrrev_i32_e32 v149, 31, v148
	v_lshlrev_b64 v[148:149], 13, v[148:149]
	v_ashrrev_i32_e32 v147, 31, v146
	v_lshl_add_u64 v[148:149], s[42:43], 0, v[148:149]
	v_lshlrev_b64 v[152:153], 12, v[146:147]
	v_pk_fma_f32 v[42:43], v[42:43], v[130:131], v[168:169]
	v_pk_fma_f32 v[40:41], v[40:41], v[128:129], v[166:167]
	v_lshl_add_u64 v[154:155], v[148:149], 0, v[242:243]
	v_pk_mul_f32 v[150:151], v[234:235], v[46:47]
	v_pk_mul_f32 v[148:149], v[236:237], v[44:45]
	v_pk_mul_f32 v[156:157], v[238:239], v[42:43]
	v_pk_mul_f32 v[158:159], v[240:241], v[40:41]
	v_lshl_add_u64 v[152:153], s[20:21], 0, v[152:153]
	v_cvt_pk_bf16_f32 v148, v148, v149
	v_cvt_pk_bf16_f32 v149, v150, v151
	v_cvt_pk_bf16_f32 v150, v158, v159
	v_cvt_pk_bf16_f32 v151, v156, v157
	v_lshl_add_u64 v[152:153], v[152:153], 0, v[200:201]
	s_waitcnt vmcnt(14)
; __device__ __forceinline__ unsigned pk2(float lo, float hi) { const f32x2 v = {lo, hi}; return __builtin_bit_cast(unsigned, __builtin_convertvector(v, bf16x2_t)); }
;     __device__ __forceinline__ void operator()(const f32x4 (&acc)[2][2][4][2], const Unit& un, int wr, int wc, int fr_, int fq_) const {
;     ...
; #pragma unroll
;             for (int m = 0; m < 4; ++m)
; #pragma unroll
;                 for (int bj = 0; bj < 2; ++bj) { const int row = rbase + ai * 128 + m * 16, col = cw + bj * 128; const f32x4 v0 = acc[ai][bj][m][0], v1 = acc[ai][bj][m][1];
;                     float* dp = dst + (size_t)(row - radj) * D + col;
;                     const f32x4 x0 = xa[m][bj][0] + g0[bj] * v0, x1 = xa[m][bj][1] + g1[bj] * v1;
;                     *(f32x4*)dp = x0; *(f32x4*)(dp + 4) = x1;
;                     ssq[ai][m] += (x0.x * x0.x + x0.y * x0.y) + (x0.z * x0.z + x0.w * x0.w) + (x1.x * x1.x + x1.y * x1.y) + (x1.z * x1.z + x1.w * x1.w);
;                     const f32x4 y0 = x0 * y0s[bj], y1 = x1 * y1s[bj];
;                     u32x4 w; w.x = pk2(y0.x, y0.y); w.y = pk2(y0.z, y0.w); w.z = pk2(y1.x, y1.y); w.w = pk2(y1.z, y1.w); *(u32x4*)(xg + (size_t)row * D + col) = w; } }
; #pragma unroll
;         for (int ai = 0; ai < 2; ++ai)
; #pragma unroll
;             for (int m = 0; m < 4; ++m) { float s = ssq[ai][m]; s += shx<16>(s); s += shx<32>(s);
;                 if (fq == 0) ps[((size_t)(rbase + ai * 128 + m * 16) * 8 + un.pn) * 4 + wc] = s; }
	v_pk_fma_f32 v[38:39], v[38:39], v[126:127], v[184:185]
	v_pk_fma_f32 v[36:37], v[36:37], v[124:125], v[182:183]
	v_pk_fma_f32 v[34:35], v[34:35], v[118:119], v[180:181]
	v_pk_fma_f32 v[32:33], v[32:33], v[116:117], v[178:179]
	global_store_dwordx4 v[154:155], v[44:47], off
	global_store_dwordx4 v[154:155], v[40:43], off offset:16
	global_store_dwordx4 v[152:153], v[148:151], off
	global_store_dwordx4 v[154:155], v[36:39], off offset:512
	global_store_dwordx4 v[154:155], v[32:35], off offset:528
	v_pk_mul_f32 v[150:151], v[226:227], v[38:39]
	v_pk_mul_f32 v[148:149], v[228:229], v[36:37]
	v_pk_mul_f32 v[154:155], v[230:231], v[34:35]
	v_pk_mul_f32 v[156:157], v[232:233], v[32:33]
	v_cvt_pk_bf16_f32 v148, v148, v149
	v_cvt_pk_bf16_f32 v149, v150, v151
	v_cvt_pk_bf16_f32 v150, v156, v157
	v_cvt_pk_bf16_f32 v151, v154, v155
	global_store_dwordx4 v[152:153], v[148:151], off offset:256
	s_waitcnt vmcnt(18)
	v_pk_fma_f32 v[30:31], v[30:31], v[134:135], v[198:199]
	v_pk_fma_f32 v[28:29], v[28:29], v[132:133], v[196:197]
	v_add_u32_e32 v148, 0xa0, v224
	v_subrev_u32_e32 v150, s29, v148
	v_ashrrev_i32_e32 v151, 31, v150
	v_lshlrev_b64 v[150:151], 13, v[150:151]
	v_ashrrev_i32_e32 v149, 31, v148
	v_lshl_add_u64 v[150:151], s[42:43], 0, v[150:151]
	v_lshlrev_b64 v[154:155], 12, v[148:149]
	v_pk_fma_f32 v[26:27], v[26:27], v[130:131], v[188:189]
	v_pk_fma_f32 v[24:25], v[24:25], v[128:129], v[186:187]
	v_lshl_add_u64 v[156:157], v[150:151], 0, v[242:243]
	v_pk_mul_f32 v[152:153], v[234:235], v[30:31]
	v_pk_mul_f32 v[150:151], v[236:237], v[28:29]
	v_pk_mul_f32 v[158:159], v[238:239], v[26:27]
	v_pk_mul_f32 v[162:163], v[240:241], v[24:25]
	v_lshl_add_u64 v[154:155], s[20:21], 0, v[154:155]
	v_cvt_pk_bf16_f32 v150, v150, v151
	v_cvt_pk_bf16_f32 v151, v152, v153
	v_cvt_pk_bf16_f32 v152, v162, v163
	v_cvt_pk_bf16_f32 v153, v158, v159
	v_lshl_add_u64 v[154:155], v[154:155], 0, v[200:201]
	s_waitcnt vmcnt(16)
	v_pk_fma_f32 v[22:23], v[22:23], v[126:127], v[250:251]
	v_pk_fma_f32 v[20:21], v[20:21], v[124:125], v[248:249]
	v_pk_fma_f32 v[18:19], v[18:19], v[118:119], v[204:205]
	v_pk_fma_f32 v[16:17], v[16:17], v[116:117], v[202:203]
	global_store_dwordx4 v[156:157], v[28:31], off
	global_store_dwordx4 v[156:157], v[24:27], off offset:16
	global_store_dwordx4 v[154:155], v[150:153], off
	global_store_dwordx4 v[156:157], v[20:23], off offset:512
	global_store_dwordx4 v[156:157], v[16:19], off offset:528
	v_pk_mul_f32 v[152:153], v[226:227], v[22:23]
	v_pk_mul_f32 v[150:151], v[228:229], v[20:21]
	v_pk_mul_f32 v[156:157], v[230:231], v[18:19]
	v_pk_mul_f32 v[158:159], v[232:233], v[16:17]
	v_cvt_pk_bf16_f32 v150, v150, v151
	v_cvt_pk_bf16_f32 v151, v152, v153
	v_cvt_pk_bf16_f32 v152, v158, v159
	v_cvt_pk_bf16_f32 v153, v156, v157
	global_store_dwordx4 v[154:155], v[150:153], off offset:256
	s_waitcnt vmcnt(20)
	v_pk_fma_f32 v[14:15], v[14:15], v[134:135], v[142:143]
	v_pk_fma_f32 v[12:13], v[12:13], v[132:133], v[140:141]
	v_add_u32_e32 v150, 0xb0, v224
	v_subrev_u32_e32 v152, s29, v150
	v_ashrrev_i32_e32 v153, 31, v152
	v_ashrrev_i32_e32 v151, 31, v150
	v_pk_fma_f32 v[10:11], v[10:11], v[130:131], v[138:139]
	v_lshlrev_b64 v[152:153], 13, v[152:153]
	v_lshlrev_b64 v[154:155], 12, v[150:151]
	v_pk_fma_f32 v[8:9], v[8:9], v[128:129], v[136:137]
	v_pk_mul_f32 v[130:131], v[234:235], v[14:15]
	v_pk_mul_f32 v[128:129], v[236:237], v[12:13]
	v_pk_mul_f32 v[132:133], v[238:239], v[10:11]
	s_waitcnt vmcnt(18)
	v_pk_fma_f32 v[6:7], v[6:7], v[126:127], v[122:123]
	v_pk_fma_f32 v[4:5], v[4:5], v[124:125], v[120:121]
	v_pk_fma_f32 v[2:3], v[2:3], v[118:119], v[114:115]
	v_pk_fma_f32 v[0:1], v[0:1], v[116:117], v[112:113]
	v_lshl_add_u64 v[152:153], s[42:43], 0, v[152:153]
	v_pk_mul_f32 v[134:135], v[240:241], v[8:9]
	v_cvt_pk_bf16_f32 v128, v128, v129
	v_cvt_pk_bf16_f32 v129, v130, v131
	v_cvt_pk_bf16_f32 v131, v132, v133
	v_lshl_add_u64 v[132:133], s[20:21], 0, v[154:155]
	v_pk_mul_f32 v[114:115], v[226:227], v[6:7]
	v_pk_mul_f32 v[112:113], v[228:229], v[4:5]
	v_pk_mul_f32 v[116:117], v[230:231], v[2:3]
	v_pk_mul_f32 v[118:119], v[232:233], v[0:1]
	v_lshl_add_u64 v[152:153], v[152:153], 0, v[242:243]
	v_cvt_pk_bf16_f32 v130, v134, v135
	v_lshl_add_u64 v[132:133], v[132:133], 0, v[200:201]
	v_cvt_pk_bf16_f32 v112, v112, v113
	v_cvt_pk_bf16_f32 v113, v114, v115
	v_cvt_pk_bf16_f32 v114, v118, v119
	v_cvt_pk_bf16_f32 v115, v116, v117
	global_store_dwordx4 v[152:153], v[12:15], off
	global_store_dwordx4 v[152:153], v[8:11], off offset:16
	global_store_dwordx4 v[132:133], v[128:131], off
	global_store_dwordx4 v[152:153], v[4:7], off offset:512
	global_store_dwordx4 v[152:153], v[0:3], off offset:528
	global_store_dwordx4 v[132:133], v[112:115], off offset:256
	ds_swizzle_b32 v112, v194 offset:swizzle(SWAP,16)
	s_nop 0
	v_mbcnt_lo_u32_b32 v113, -1, 0
	v_mbcnt_hi_u32_b32 v113, -1, v113
	s_waitcnt lgkmcnt(0)
	v_add_f32_e32 v112, v194, v112
	v_lshlrev_b32_e32 v113, 2, v113
	v_xor_b32_e32 v113, 0x80, v113
	ds_bpermute_b32 v113, v113, v112
	s_and_saveexec_b64 s[40:41], vcc
	s_mov_b32 s74, 0x240000
	s_cbranch_execz .LBB0_1324
	v_lshlrev_b64 v[114:115], 7, v[224:225]
	v_lshl_add_u64 v[114:115], s[24:25], 0, v[114:115]
	v_lshl_add_u64 v[114:115], v[114:115], 0, s[38:39]
	s_mov_b32 s43, s91
	s_lshl_b32 s42, s63, 2
	v_lshl_add_u64 v[114:115], v[114:115], 0, s[42:43]
	s_waitcnt lgkmcnt(0)
	v_add_f32_e32 v112, v112, v113
	global_store_dword v[114:115], v112, off

;     __device__ __forceinline__ void operator()(const f32x4 (&acc)[2][2][4][2], const Unit& un, int wr, int wc, int fr_, int fq_) const {
;     ...
;         const int rbase = un.pm * 256 + wr * 64 + fr, cw = un.pn * 256 + wc * 32 + 8 * fq;
;         const bool lat = un.pm < (NLAT / 256);
;         const int slot = lat ? (un.pm >> 5) : 4;
;         const float* src = lat ? srcl : srcc; float* dst = lat ? dstl : dstc; const int radj = lat ? 0 : NLAT;
;         const float* gp = modg + (size_t)slot * 12288; const float* sp2 = sc2 + (size_t)slot * 12288;
;         float ssq[2][4];
; #pragma unroll
;         for (int ai = 0; ai < 2; ++ai)
; #pragma unroll
;             for (int m = 0; m < 4; ++m) ssq[ai][m] = 0.f;
;         f32x4 g0[2], g1[2], y0s[2], y1s[2];
; #pragma unroll
;         for (int bj = 0; bj < 2; ++bj) { const int col = cw + bj * 128; g0[bj] = *(const f32x4*)(gp + col); g1[bj] = *(const f32x4*)(gp + col + 4);
;             y0s[bj] = *(const f32x4*)(ng2 + col) * (*(const f32x4*)(sp2 + col) + 1.f); y1s[bj] = *(const f32x4*)(ng2 + col + 4) * (*(const f32x4*)(sp2 + col + 4) + 1.f); }
; #pragma unroll
;         for (int ai = 0; ai < 2; ++ai) {
;             f32x4 xa[4][2][2];
; #pragma unroll
;             for (int m = 0; m < 4; ++m)
; #pragma unroll
;                 for (int bj = 0; bj < 2; ++bj) { const float* sp = src + (size_t)(rbase + ai * 128 + m * 16 - radj) * D + cw + bj * 128; xa[m][bj][0] = *(const f32x4*)sp; xa[m][bj][1] = *(const f32x4*)(sp + 4); }
; #pragma unroll
;             for (int m = 0; m < 4; ++m)
; #pragma unroll
;                 for (int bj = 0; bj < 2; ++bj) { const int row = rbase + ai * 128 + m * 16, col = cw + bj * 128; const f32x4 v0 = acc[ai][bj][m][0], v1 = acc[ai][bj][m][1];
;                     float* dp = dst + (size_t)(row - radj) * D + col;
;                     const f32x4 x0 = xa[m][bj][0] + g0[bj] * v0, x1 = xa[m][bj][1] + g1[bj] * v1;
;                     *(f32x4*)dp = x0; *(f32x4*)(dp + 4) = x1;
;                     ssq[ai][m] += (x0.x * x0.x + x0.y * x0.y) + (x0.z * x0.z + x0.w * x0.w) + (x1.x * x1.x + x1.y * x1.y) + (x1.z * x1.z + x1.w * x1.w);
;                     const f32x4 y0 = x0 * y0s[bj], y1 = x1 * y1s[bj];
;                     u32x4 w; w.x = pk2(y0.x, y0.y); w.y = pk2(y0.z, y0.w); w.z = pk2(y1.x, y1.y); w.w = pk2(y1.z, y1.w); *(u32x4*)(xg + (size_t)row * D + col) = w; } }
.LBB0_1565:
	s_lshl_b32 s31, s40, 8
	s_add_i32 s31, s31, s64
	v_and_or_b32 v224, v211, 15, s31
	s_lshl_b32 s31, s38, 8
	s_or_b32 s31, s31, s65
	v_ashrrev_i32_e32 v116, 1, v211
	s_lshl_b64 s[40:41], s[46:47], 2
	v_and_b32_e32 v116, -8, v116
	s_add_u32 s46, s59, s40
	v_add_u32_e32 v248, s31, v116
	s_addc_u32 s47, s60, s41
	s_add_u32 s40, s61, s40
	v_ashrrev_i32_e32 v249, 31, v248
	s_addc_u32 s41, s62, s41
	v_lshlrev_b64 v[242:243], 2, v[248:249]
	v_lshl_add_u64 v[152:153], s[46:47], 0, v[242:243]
	v_lshl_add_u64 v[154:155], s[22:23], 0, v[242:243]
	v_lshl_add_u64 v[156:157], s[40:41], 0, v[242:243]
	global_load_dwordx4 v[128:131], v[152:153], off offset:16
	global_load_dwordx4 v[132:135], v[152:153], off
	global_load_dwordx4 v[116:119], v[154:155], off offset:16
	global_load_dwordx4 v[124:127], v[154:155], off
	global_load_dwordx4 v[144:147], v[156:157], off offset:16
	global_load_dwordx4 v[148:151], v[156:157], off
	v_subrev_u32_e32 v246, s29, v224
	v_ashrrev_i32_e32 v247, 31, v246
	v_lshl_add_u64 v[244:245], s[44:45], 0, v[242:243]
	v_lshlrev_b64 v[212:213], 13, v[246:247]
	v_lshl_add_u64 v[226:227], v[244:245], 0, v[212:213]
	global_load_dwordx4 v[200:203], v[226:227], off offset:16
	global_load_dwordx4 v[204:207], v[226:227], off
	global_load_dwordx4 v[192:195], v[226:227], off offset:528
	global_load_dwordx4 v[196:199], v[226:227], off offset:512
	v_or_b32_e32 v228, 16, v246
	v_ashrrev_i32_e32 v229, 31, v228
	v_lshlrev_b64 v[228:229], 13, v[228:229]
	v_lshl_add_u64 v[228:229], v[244:245], 0, v[228:229]
	global_load_dwordx4 v[184:187], v[228:229], off offset:16
	global_load_dwordx4 v[188:191], v[228:229], off
	global_load_dwordx4 v[176:179], v[228:229], off offset:528
	global_load_dwordx4 v[180:183], v[228:229], off offset:512
	v_or_b32_e32 v230, 32, v246
	v_ashrrev_i32_e32 v231, 31, v230
	v_lshlrev_b64 v[230:231], 13, v[230:231]
	v_lshl_add_u64 v[230:231], v[244:245], 0, v[230:231]
	global_load_dwordx4 v[168:171], v[230:231], off offset:16
	global_load_dwordx4 v[172:175], v[230:231], off
	global_load_dwordx4 v[160:163], v[230:231], off offset:528
	global_load_dwordx4 v[164:167], v[230:231], off offset:512
	s_and_b64 vcc, exec, s[26:27]
	s_cbranch_vccz .LBB0_1562
	s_barrier
.LBB0_1562:
	v_ashrrev_i32_e32 v225, 31, v224
	v_lshlrev_b64 v[250:251], 12, v[224:225]
	s_ashr_i32 s39, s38, 31
	v_cmp_gt_u32_e32 vcc, 16, v211
	s_lshl_b64 s[38:39], s[38:39], 4
	s_waitcnt vmcnt(12)
	v_pk_add_f32 v[150:151], v[150:151], 1.0 op_sel_hi:[1,0]
	v_pk_add_f32 v[148:149], v[148:149], 1.0 op_sel_hi:[1,0]
	v_pk_mul_f32 v[234:235], v[126:127], v[150:151]
	v_pk_mul_f32 v[236:237], v[124:125], v[148:149]
	v_pk_add_f32 v[124:125], v[146:147], 1.0 op_sel_hi:[1,0]
	v_pk_add_f32 v[126:127], v[144:145], 1.0 op_sel_hi:[1,0]
	v_pk_mul_f32 v[238:239], v[118:119], v[124:125]
	v_pk_mul_f32 v[240:241], v[116:117], v[126:127]
	global_load_dwordx4 v[116:119], v[152:153], off offset:528
	global_load_dwordx4 v[124:127], v[152:153], off offset:512
	global_load_dwordx4 v[144:147], v[154:155], off offset:528
	global_load_dwordx4 v[148:151], v[154:155], off offset:512
	s_nop 0
	global_load_dwordx4 v[152:155], v[156:157], off offset:528
	s_nop 0
	global_load_dwordx4 v[156:159], v[156:157], off offset:512
	s_waitcnt vmcnt(0)
	v_pk_add_f32 v[158:159], v[158:159], 1.0 op_sel_hi:[1,0]
	s_nop 0
	v_pk_mul_f32 v[226:227], v[150:151], v[158:159]
	v_pk_add_f32 v[150:151], v[152:153], 1.0 op_sel_hi:[1,0]
	v_pk_add_f32 v[156:157], v[156:157], 1.0 op_sel_hi:[1,0]
	v_pk_mul_f32 v[232:233], v[144:145], v[150:151]
	v_or_b32_e32 v144, 48, v246
	v_ashrrev_i32_e32 v145, 31, v144
	v_pk_mul_f32 v[228:229], v[148:149], v[156:157]
	v_pk_add_f32 v[148:149], v[154:155], 1.0 op_sel_hi:[1,0]
	v_lshlrev_b64 v[144:145], 13, v[144:145]
	v_pk_mul_f32 v[230:231], v[146:147], v[148:149]
	v_lshl_add_u64 v[148:149], v[244:245], 0, v[144:145]
	global_load_dwordx4 v[152:155], v[148:149], off offset:16
	global_load_dwordx4 v[156:159], v[148:149], off
	global_load_dwordx4 v[144:147], v[148:149], off offset:528
	s_nop 0
	global_load_dwordx4 v[148:151], v[148:149], off offset:512
	v_lshl_add_u64 v[212:213], s[42:43], 0, v[212:213]
	v_lshl_add_u64 v[212:213], v[212:213], 0, v[242:243]
	s_nop 0
	v_pk_fma_f32 v[136:137], v[136:137], v[128:129], v[200:201]
	s_nop 0
	v_pk_fma_f32 v[142:143], v[142:143], v[134:135], v[206:207]
	v_pk_fma_f32 v[140:141], v[140:141], v[132:133], v[204:205]
	v_mul_f32_e32 v201, v143, v143
	v_mul_f32_e32 v200, v141, v141
	v_fmac_f32_e32 v200, v140, v140
	v_fmac_f32_e32 v201, v142, v142
	v_add_f32_e32 v200, v200, v201
	v_mul_f32_e32 v201, v137, v137
	v_pk_fma_f32 v[138:139], v[138:139], v[130:131], v[202:203]
	v_fmac_f32_e32 v201, v136, v136
	v_add_f32_e32 v200, v200, v201
	v_mul_f32_e32 v201, v139, v139
	v_fmac_f32_e32 v201, v138, v138
	global_store_dwordx4 v[212:213], v[140:143], off
	global_store_dwordx4 v[212:213], v[136:139], off offset:16
	v_add_f32_e32 v202, v201, v200
	v_pk_mul_f32 v[140:141], v[236:237], v[140:141]
	v_pk_mul_f32 v[200:201], v[238:239], v[138:139]
	v_pk_mul_f32 v[138:139], v[240:241], v[136:137]
	v_pk_mul_f32 v[142:143], v[234:235], v[142:143]
	v_cvt_pk_bf16_f32 v136, v140, v141
	v_cvt_pk_bf16_f32 v138, v138, v139
	v_cvt_pk_bf16_f32 v139, v200, v201
	v_lshl_add_u64 v[140:141], s[20:21], 0, v[250:251]
	v_lshlrev_b64 v[200:201], 1, v[248:249]
	v_cvt_pk_bf16_f32 v137, v142, v143
	v_lshl_add_u64 v[140:141], v[140:141], 0, v[200:201]
	s_nop 0
	v_pk_fma_f32 v[122:123], v[122:123], v[126:127], v[198:199]
	v_pk_fma_f32 v[120:121], v[120:121], v[124:125], v[196:197]
	global_store_dwordx4 v[140:141], v[136:139], off
	v_pk_fma_f32 v[112:113], v[112:113], v[116:117], v[192:193]
; __device__ __forceinline__ unsigned pk2(float lo, float hi) { const f32x2 v = {lo, hi}; return __builtin_bit_cast(unsigned, __builtin_convertvector(v, bf16x2_t)); }
;     __device__ __forceinline__ void operator()(const f32x4 (&acc)[2][2][4][2], const Unit& un, int wr, int wc, int fr_, int fq_) const {
;     ...
; #pragma unroll
;             for (int m = 0; m < 4; ++m)
; #pragma unroll
;                 for (int bj = 0; bj < 2; ++bj) { const int row = rbase + ai * 128 + m * 16, col = cw + bj * 128; const f32x4 v0 = acc[ai][bj][m][0], v1 = acc[ai][bj][m][1];
;                     float* dp = dst + (size_t)(row - radj) * D + col;
;                     const f32x4 x0 = xa[m][bj][0] + g0[bj] * v0, x1 = xa[m][bj][1] + g1[bj] * v1;
;                     *(f32x4*)dp = x0; *(f32x4*)(dp + 4) = x1;
;                     ssq[ai][m] += (x0.x * x0.x + x0.y * x0.y) + (x0.z * x0.z + x0.w * x0.w) + (x1.x * x1.x + x1.y * x1.y) + (x1.z * x1.z + x1.w * x1.w);
;                     const f32x4 y0 = x0 * y0s[bj], y1 = x1 * y1s[bj];
;                     u32x4 w; w.x = pk2(y0.x, y0.y); w.y = pk2(y0.z, y0.w); w.z = pk2(y1.x, y1.y); w.w = pk2(y1.z, y1.w); *(u32x4*)(xg + (size_t)row * D + col) = w; } }
	v_pk_fma_f32 v[114:115], v[114:115], v[118:119], v[194:195]
	v_mul_f32_e32 v136, v121, v121
	v_mul_f32_e32 v137, v123, v123
	v_fmac_f32_e32 v136, v120, v120
	v_fmac_f32_e32 v137, v122, v122
	v_add_f32_e32 v136, v136, v137
	v_mul_f32_e32 v137, v113, v113
	v_fmac_f32_e32 v137, v112, v112
	v_add_f32_e32 v136, v136, v137
	v_mul_f32_e32 v137, v115, v115
	v_fmac_f32_e32 v137, v114, v114
	v_add_f32_e32 v136, v137, v136
	global_store_dwordx4 v[212:213], v[120:123], off offset:512
	global_store_dwordx4 v[212:213], v[112:115], off offset:528
	v_add_f32_e32 v194, v202, v136
	v_pk_mul_f32 v[122:123], v[226:227], v[122:123]
	v_pk_mul_f32 v[120:121], v[228:229], v[120:121]
	v_pk_mul_f32 v[136:137], v[230:231], v[114:115]
	v_pk_mul_f32 v[114:115], v[232:233], v[112:113]
	v_cvt_pk_bf16_f32 v112, v120, v121
	v_cvt_pk_bf16_f32 v113, v122, v123
	v_cvt_pk_bf16_f32 v114, v114, v115
	v_cvt_pk_bf16_f32 v115, v136, v137
	v_or_b32_e32 v192, 16, v224
	global_store_dwordx4 v[140:141], v[112:115], off offset:256
	v_ashrrev_i32_e32 v193, 31, v192
	v_lshlrev_b64 v[120:121], 12, v[192:193]
	v_subrev_u32_e32 v112, s29, v192
	v_ashrrev_i32_e32 v113, 31, v112
	v_lshlrev_b64 v[112:113], 13, v[112:113]
	v_lshl_add_u64 v[112:113], s[42:43], 0, v[112:113]
	s_nop 0
	v_pk_fma_f32 v[110:111], v[110:111], v[134:135], v[190:191]
	v_pk_fma_f32 v[108:109], v[108:109], v[132:133], v[188:189]
	v_pk_fma_f32 v[106:107], v[106:107], v[130:131], v[186:187]
	v_pk_fma_f32 v[104:105], v[104:105], v[128:129], v[184:185]
	v_lshl_add_u64 v[122:123], v[112:113], 0, v[242:243]
	v_pk_mul_f32 v[114:115], v[234:235], v[110:111]
	v_pk_mul_f32 v[112:113], v[236:237], v[108:109]
	v_pk_mul_f32 v[136:137], v[238:239], v[106:107]
	v_pk_mul_f32 v[138:139], v[240:241], v[104:105]
	v_lshl_add_u64 v[120:121], s[20:21], 0, v[120:121]
	v_cvt_pk_bf16_f32 v112, v112, v113
	v_cvt_pk_bf16_f32 v113, v114, v115
	v_cvt_pk_bf16_f32 v114, v138, v139
	v_cvt_pk_bf16_f32 v115, v136, v137
	v_lshl_add_u64 v[120:121], v[120:121], 0, v[200:201]
	s_nop 0
	v_pk_fma_f32 v[102:103], v[102:103], v[126:127], v[182:183]
	v_pk_fma_f32 v[100:101], v[100:101], v[124:125], v[180:181]
	v_pk_fma_f32 v[98:99], v[98:99], v[118:119], v[178:179]
	v_pk_fma_f32 v[96:97], v[96:97], v[116:117], v[176:177]
	global_store_dwordx4 v[122:123], v[108:111], off
	global_store_dwordx4 v[122:123], v[104:107], off offset:16
	global_store_dwordx4 v[120:121], v[112:115], off
	global_store_dwordx4 v[122:123], v[100:103], off offset:512
	global_store_dwordx4 v[122:123], v[96:99], off offset:528
	v_pk_mul_f32 v[114:115], v[226:227], v[102:103]
	v_pk_mul_f32 v[112:113], v[228:229], v[100:101]
	v_pk_mul_f32 v[122:123], v[230:231], v[98:99]
	v_pk_mul_f32 v[136:137], v[232:233], v[96:97]
	v_cvt_pk_bf16_f32 v112, v112, v113
	v_cvt_pk_bf16_f32 v113, v114, v115
	v_cvt_pk_bf16_f32 v114, v136, v137
	v_cvt_pk_bf16_f32 v115, v122, v123
	v_or_b32_e32 v176, 32, v224
	global_store_dwordx4 v[120:121], v[112:115], off offset:256
	v_ashrrev_i32_e32 v177, 31, v176
	v_lshlrev_b64 v[120:121], 12, v[176:177]
	v_subrev_u32_e32 v112, s29, v176
	v_ashrrev_i32_e32 v113, 31, v112
	v_lshlrev_b64 v[112:113], 13, v[112:113]
	v_lshl_add_u64 v[112:113], s[42:43], 0, v[112:113]
	s_nop 0
	v_pk_fma_f32 v[94:95], v[94:95], v[134:135], v[174:175]
	v_pk_fma_f32 v[92:93], v[92:93], v[132:133], v[172:173]
	v_pk_fma_f32 v[90:91], v[90:91], v[130:131], v[170:171]
	v_pk_fma_f32 v[88:89], v[88:89], v[128:129], v[168:169]
	v_lshl_add_u64 v[122:123], v[112:113], 0, v[242:243]
	v_pk_mul_f32 v[114:115], v[234:235], v[94:95]
	v_pk_mul_f32 v[112:113], v[236:237], v[92:93]
	v_pk_mul_f32 v[136:137], v[238:239], v[90:91]
	v_pk_mul_f32 v[138:139], v[240:241], v[88:89]
	v_lshl_add_u64 v[120:121], s[20:21], 0, v[120:121]
	v_cvt_pk_bf16_f32 v112, v112, v113
	v_cvt_pk_bf16_f32 v113, v114, v115
	v_cvt_pk_bf16_f32 v114, v138, v139
	v_cvt_pk_bf16_f32 v115, v136, v137
	v_lshl_add_u64 v[120:121], v[120:121], 0, v[200:201]
	s_nop 0
	v_pk_fma_f32 v[86:87], v[86:87], v[126:127], v[166:167]
	v_pk_fma_f32 v[84:85], v[84:85], v[124:125], v[164:165]
	v_pk_fma_f32 v[82:83], v[82:83], v[118:119], v[162:163]
	v_pk_fma_f32 v[80:81], v[80:81], v[116:117], v[160:161]
	global_store_dwordx4 v[122:123], v[92:95], off
	global_store_dwordx4 v[122:123], v[88:91], off offset:16
	global_store_dwordx4 v[120:121], v[112:115], off
	global_store_dwordx4 v[122:123], v[84:87], off offset:512
	global_store_dwordx4 v[122:123], v[80:83], off offset:528
	v_pk_mul_f32 v[114:115], v[226:227], v[86:87]
	v_pk_mul_f32 v[112:113], v[228:229], v[84:85]
	v_pk_mul_f32 v[122:123], v[230:231], v[82:83]
	v_pk_mul_f32 v[136:137], v[232:233], v[80:81]
	v_cvt_pk_bf16_f32 v112, v112, v113
	v_cvt_pk_bf16_f32 v113, v114, v115
	v_cvt_pk_bf16_f32 v114, v136, v137
	v_cvt_pk_bf16_f32 v115, v122, v123
	v_or_b32_e32 v160, 48, v224
	global_store_dwordx4 v[120:121], v[112:115], off offset:256
	v_ashrrev_i32_e32 v161, 31, v160
	v_lshlrev_b64 v[120:121], 12, v[160:161]
	v_subrev_u32_e32 v112, s29, v160
	v_ashrrev_i32_e32 v113, 31, v112
	v_lshlrev_b64 v[112:113], 13, v[112:113]
	v_lshl_add_u64 v[112:113], s[42:43], 0, v[112:113]
	s_waitcnt vmcnt(20)
	v_pk_fma_f32 v[78:79], v[78:79], v[134:135], v[158:159]
	v_pk_fma_f32 v[76:77], v[76:77], v[132:133], v[156:157]
	v_pk_fma_f32 v[74:75], v[74:75], v[130:131], v[154:155]
	v_pk_fma_f32 v[72:73], v[72:73], v[128:129], v[152:153]
	v_lshl_add_u64 v[122:123], v[112:113], 0, v[242:243]
	v_pk_mul_f32 v[114:115], v[234:235], v[78:79]
	v_pk_mul_f32 v[112:113], v[236:237], v[76:77]
	v_pk_mul_f32 v[136:137], v[238:239], v[74:75]
	v_pk_mul_f32 v[138:139], v[240:241], v[72:73]
	v_lshl_add_u64 v[120:121], s[20:21], 0, v[120:121]
	v_cvt_pk_bf16_f32 v112, v112, v113
	v_cvt_pk_bf16_f32 v113, v114, v115
	v_cvt_pk_bf16_f32 v114, v138, v139
	v_cvt_pk_bf16_f32 v115, v136, v137
	v_lshl_add_u64 v[120:121], v[120:121], 0, v[200:201]
	s_waitcnt vmcnt(18)
; __device__ __forceinline__ unsigned pk2(float lo, float hi) { const f32x2 v = {lo, hi}; return __builtin_bit_cast(unsigned, __builtin_convertvector(v, bf16x2_t)); }
;     __device__ __forceinline__ void operator()(const f32x4 (&acc)[2][2][4][2], const Unit& un, int wr, int wc, int fr_, int fq_) const {
;     ...
;         for (int ai = 0; ai < 2; ++ai) {
;             f32x4 xa[4][2][2];
; #pragma unroll
;             for (int m = 0; m < 4; ++m)
; #pragma unroll
;                 for (int bj = 0; bj < 2; ++bj) { const float* sp = src + (size_t)(rbase + ai * 128 + m * 16 - radj) * D + cw + bj * 128; xa[m][bj][0] = *(const f32x4*)sp; xa[m][bj][1] = *(const f32x4*)(sp + 4); }
; #pragma unroll
;             for (int m = 0; m < 4; ++m)
; #pragma unroll
;                 for (int bj = 0; bj < 2; ++bj) { const int row = rbase + ai * 128 + m * 16, col = cw + bj * 128; const f32x4 v0 = acc[ai][bj][m][0], v1 = acc[ai][bj][m][1];
;                     float* dp = dst + (size_t)(row - radj) * D + col;
;                     const f32x4 x0 = xa[m][bj][0] + g0[bj] * v0, x1 = xa[m][bj][1] + g1[bj] * v1;
;                     *(f32x4*)dp = x0; *(f32x4*)(dp + 4) = x1;
;                     ssq[ai][m] += (x0.x * x0.x + x0.y * x0.y) + (x0.z * x0.z + x0.w * x0.w) + (x1.x * x1.x + x1.y * x1.y) + (x1.z * x1.z + x1.w * x1.w);
;                     const f32x4 y0 = x0 * y0s[bj], y1 = x1 * y1s[bj];
;                     u32x4 w; w.x = pk2(y0.x, y0.y); w.y = pk2(y0.z, y0.w); w.z = pk2(y1.x, y1.y); w.w = pk2(y1.z, y1.w); *(u32x4*)(xg + (size_t)row * D + col) = w; } }
	v_pk_fma_f32 v[70:71], v[70:71], v[126:127], v[150:151]
	v_pk_fma_f32 v[68:69], v[68:69], v[124:125], v[148:149]
	v_pk_fma_f32 v[66:67], v[66:67], v[118:119], v[146:147]
	v_pk_fma_f32 v[64:65], v[64:65], v[116:117], v[144:145]
	global_store_dwordx4 v[122:123], v[76:79], off
	global_store_dwordx4 v[122:123], v[72:75], off offset:16
	global_store_dwordx4 v[120:121], v[112:115], off
	global_store_dwordx4 v[122:123], v[68:71], off offset:512
	global_store_dwordx4 v[122:123], v[64:67], off offset:528
	v_pk_mul_f32 v[114:115], v[226:227], v[70:71]
	v_pk_mul_f32 v[112:113], v[228:229], v[68:69]
	v_pk_mul_f32 v[122:123], v[230:231], v[66:67]
	v_pk_mul_f32 v[136:137], v[232:233], v[64:65]
	v_cvt_pk_bf16_f32 v112, v112, v113
	v_cvt_pk_bf16_f32 v113, v114, v115
	v_cvt_pk_bf16_f32 v114, v136, v137
	v_cvt_pk_bf16_f32 v115, v122, v123
	global_store_dwordx4 v[120:121], v[112:115], off offset:256
	v_add_u32_e32 v144, 0x80, v224
	v_subrev_u32_e32 v158, s29, v144
	v_add_u32_e32 v112, 0x80, v246
	v_ashrrev_i32_e32 v113, 31, v112
	v_lshlrev_b64 v[112:113], 13, v[112:113]
	v_lshl_add_u64 v[112:113], v[244:245], 0, v[112:113]
	global_load_dwordx4 v[146:149], v[112:113], off offset:16
	global_load_dwordx4 v[150:153], v[112:113], off
	global_load_dwordx4 v[154:157], v[112:113], off offset:528
	global_load_dwordx4 v[162:165], v[112:113], off offset:512
	v_add_u32_e32 v112, 0x90, v246
	v_ashrrev_i32_e32 v113, 31, v112
	v_lshlrev_b64 v[112:113], 13, v[112:113]
	v_lshl_add_u64 v[112:113], v[244:245], 0, v[112:113]
	global_load_dwordx4 v[166:169], v[112:113], off offset:16
	global_load_dwordx4 v[170:173], v[112:113], off
	global_load_dwordx4 v[178:181], v[112:113], off offset:528
	global_load_dwordx4 v[182:185], v[112:113], off offset:512
	v_add_u32_e32 v112, 0xa0, v246
	v_ashrrev_i32_e32 v113, 31, v112
	v_lshlrev_b64 v[112:113], 13, v[112:113]
	v_lshl_add_u64 v[112:113], v[244:245], 0, v[112:113]
	global_load_dwordx4 v[186:189], v[112:113], off offset:16
	global_load_dwordx4 v[196:199], v[112:113], off
	global_load_dwordx4 v[202:205], v[112:113], off offset:528
	global_load_dwordx4 v[248:251], v[112:113], off offset:512
	v_add_u32_e32 v112, 0xb0, v246
	v_ashrrev_i32_e32 v113, 31, v112
	v_lshlrev_b64 v[112:113], 13, v[112:113]
	v_lshl_add_u64 v[120:121], v[244:245], 0, v[112:113]
	global_load_dwordx4 v[136:139], v[120:121], off offset:16
	global_load_dwordx4 v[140:143], v[120:121], off
	global_load_dwordx4 v[112:115], v[120:121], off offset:528
	s_nop 0
	global_load_dwordx4 v[120:123], v[120:121], off offset:512
	v_ashrrev_i32_e32 v159, 31, v158
	v_ashrrev_i32_e32 v145, 31, v144
	v_lshlrev_b64 v[158:159], 13, v[158:159]
	v_lshlrev_b64 v[174:175], 12, v[144:145]
	v_lshl_add_u64 v[158:159], s[42:43], 0, v[158:159]
	v_lshl_add_u64 v[158:159], v[158:159], 0, v[242:243]
	s_waitcnt vmcnt(15)
	v_pk_fma_f32 v[58:59], v[58:59], v[130:131], v[148:149]
	s_waitcnt vmcnt(14)
	v_pk_fma_f32 v[62:63], v[62:63], v[134:135], v[152:153]
	v_pk_fma_f32 v[60:61], v[60:61], v[132:133], v[150:151]
	v_pk_fma_f32 v[56:57], v[56:57], v[128:129], v[146:147]
	v_pk_mul_f32 v[148:149], v[234:235], v[62:63]
	v_pk_mul_f32 v[146:147], v[236:237], v[60:61]
	v_pk_mul_f32 v[150:151], v[238:239], v[58:59]
	v_pk_mul_f32 v[152:153], v[240:241], v[56:57]
	v_cvt_pk_bf16_f32 v146, v146, v147
	v_cvt_pk_bf16_f32 v147, v148, v149
	v_cvt_pk_bf16_f32 v149, v150, v151
	v_lshl_add_u64 v[150:151], s[20:21], 0, v[174:175]
	v_cvt_pk_bf16_f32 v148, v152, v153
	v_lshl_add_u64 v[150:151], v[150:151], 0, v[200:201]
	s_waitcnt vmcnt(12)
	v_pk_fma_f32 v[54:55], v[54:55], v[126:127], v[164:165]
	v_pk_fma_f32 v[52:53], v[52:53], v[124:125], v[162:163]
	v_pk_fma_f32 v[50:51], v[50:51], v[118:119], v[156:157]
	v_pk_fma_f32 v[48:49], v[48:49], v[116:117], v[154:155]
	global_store_dwordx4 v[158:159], v[60:63], off
	global_store_dwordx4 v[158:159], v[56:59], off offset:16
	global_store_dwordx4 v[150:151], v[146:149], off
	v_pk_mul_f32 v[152:153], v[230:231], v[50:51]
	v_pk_mul_f32 v[154:155], v[232:233], v[48:49]
	v_pk_mul_f32 v[148:149], v[226:227], v[54:55]
	v_pk_mul_f32 v[146:147], v[228:229], v[52:53]
	global_store_dwordx4 v[158:159], v[52:55], off offset:512
	global_store_dwordx4 v[158:159], v[48:51], off offset:528
	v_cvt_pk_bf16_f32 v146, v146, v147
	v_cvt_pk_bf16_f32 v147, v148, v149
	v_cvt_pk_bf16_f32 v148, v154, v155
	v_cvt_pk_bf16_f32 v149, v152, v153
	global_store_dwordx4 v[150:151], v[146:149], off offset:256
	s_waitcnt vmcnt(16)
	v_pk_fma_f32 v[46:47], v[46:47], v[134:135], v[172:173]
	v_pk_fma_f32 v[44:45], v[44:45], v[132:133], v[170:171]
	v_add_u32_e32 v146, 0x90, v224
	v_subrev_u32_e32 v148, s29, v146
	v_ashrrev_i32_e32 v149, 31, v148
	v_lshlrev_b64 v[148:149], 13, v[148:149]
	v_ashrrev_i32_e32 v147, 31, v146
	v_lshl_add_u64 v[148:149], s[42:43], 0, v[148:149]
	v_lshlrev_b64 v[152:153], 12, v[146:147]
	v_pk_fma_f32 v[42:43], v[42:43], v[130:131], v[168:169]
	v_pk_fma_f32 v[40:41], v[40:41], v[128:129], v[166:167]
	v_lshl_add_u64 v[154:155], v[148:149], 0, v[242:243]
	v_pk_mul_f32 v[150:151], v[234:235], v[46:47]
	v_pk_mul_f32 v[148:149], v[236:237], v[44:45]
	v_pk_mul_f32 v[156:157], v[238:239], v[42:43]
	v_pk_mul_f32 v[158:159], v[240:241], v[40:41]
	v_lshl_add_u64 v[152:153], s[20:21], 0, v[152:153]
	v_cvt_pk_bf16_f32 v148, v148, v149
	v_cvt_pk_bf16_f32 v149, v150, v151
	v_cvt_pk_bf16_f32 v150, v158, v159
	v_cvt_pk_bf16_f32 v151, v156, v157
	v_lshl_add_u64 v[152:153], v[152:153], 0, v[200:201]
	s_waitcnt vmcnt(14)
; __device__ __forceinline__ unsigned pk2(float lo, float hi) { const f32x2 v = {lo, hi}; return __builtin_bit_cast(unsigned, __builtin_convertvector(v, bf16x2_t)); }
;     __device__ __forceinline__ void operator()(const f32x4 (&acc)[2][2][4][2], const Unit& un, int wr, int wc, int fr_, int fq_) const {
;     ...
; #pragma unroll
;             for (int m = 0; m < 4; ++m)
; #pragma unroll
;                 for (int bj = 0; bj < 2; ++bj) { const int row = rbase + ai * 128 + m * 16, col = cw + bj * 128; const f32x4 v0 = acc[ai][bj][m][0], v1 = acc[ai][bj][m][1];
;                     float* dp = dst + (size_t)(row - radj) * D + col;
;                     const f32x4 x0 = xa[m][bj][0] + g0[bj] * v0, x1 = xa[m][bj][1] + g1[bj] * v1;
;                     *(f32x4*)dp = x0; *(f32x4*)(dp + 4) = x1;
;                     ssq[ai][m] += (x0.x * x0.x + x0.y * x0.y) + (x0.z * x0.z + x0.w * x0.w) + (x1.x * x1.x + x1.y * x1.y) + (x1.z * x1.z + x1.w * x1.w);
;                     const f32x4 y0 = x0 * y0s[bj], y1 = x1 * y1s[bj];
;                     u32x4 w; w.x = pk2(y0.x, y0.y); w.y = pk2(y0.z, y0.w); w.z = pk2(y1.x, y1.y); w.w = pk2(y1.z, y1.w); *(u32x4*)(xg + (size_t)row * D + col) = w; } }
; #pragma unroll
;         for (int ai = 0; ai < 2; ++ai)
; #pragma unroll
;             for (int m = 0; m < 4; ++m) { float s = ssq[ai][m]; s += shx<16>(s); s += shx<32>(s);
;                 if (fq == 0) ps[((size_t)(rbase + ai * 128 + m * 16) * 8 + un.pn) * 4 + wc] = s; }
	v_pk_fma_f32 v[38:39], v[38:39], v[126:127], v[184:185]
	v_pk_fma_f32 v[36:37], v[36:37], v[124:125], v[182:183]
	v_pk_fma_f32 v[34:35], v[34:35], v[118:119], v[180:181]
	v_pk_fma_f32 v[32:33], v[32:33], v[116:117], v[178:179]
	global_store_dwordx4 v[154:155], v[44:47], off
	global_store_dwordx4 v[154:155], v[40:43], off offset:16
	global_store_dwordx4 v[152:153], v[148:151], off
	global_store_dwordx4 v[154:155], v[36:39], off offset:512
	global_store_dwordx4 v[154:155], v[32:35], off offset:528
	v_pk_mul_f32 v[150:151], v[226:227], v[38:39]
	v_pk_mul_f32 v[148:149], v[228:229], v[36:37]
	v_pk_mul_f32 v[154:155], v[230:231], v[34:35]
	v_pk_mul_f32 v[156:157], v[232:233], v[32:33]
	v_cvt_pk_bf16_f32 v148, v148, v149
	v_cvt_pk_bf16_f32 v149, v150, v151
	v_cvt_pk_bf16_f32 v150, v156, v157
	v_cvt_pk_bf16_f32 v151, v154, v155
	global_store_dwordx4 v[152:153], v[148:151], off offset:256
	s_waitcnt vmcnt(18)
	v_pk_fma_f32 v[30:31], v[30:31], v[134:135], v[198:199]
	v_pk_fma_f32 v[28:29], v[28:29], v[132:133], v[196:197]
	v_add_u32_e32 v148, 0xa0, v224
	v_subrev_u32_e32 v150, s29, v148
	v_ashrrev_i32_e32 v151, 31, v150
	v_lshlrev_b64 v[150:151], 13, v[150:151]
	v_ashrrev_i32_e32 v149, 31, v148
	v_lshl_add_u64 v[150:151], s[42:43], 0, v[150:151]
	v_lshlrev_b64 v[154:155], 12, v[148:149]
	v_pk_fma_f32 v[26:27], v[26:27], v[130:131], v[188:189]
	v_pk_fma_f32 v[24:25], v[24:25], v[128:129], v[186:187]
	v_lshl_add_u64 v[156:157], v[150:151], 0, v[242:243]
	v_pk_mul_f32 v[152:153], v[234:235], v[30:31]
	v_pk_mul_f32 v[150:151], v[236:237], v[28:29]
	v_pk_mul_f32 v[158:159], v[238:239], v[26:27]
	v_pk_mul_f32 v[162:163], v[240:241], v[24:25]
	v_lshl_add_u64 v[154:155], s[20:21], 0, v[154:155]
	v_cvt_pk_bf16_f32 v150, v150, v151
	v_cvt_pk_bf16_f32 v151, v152, v153
	v_cvt_pk_bf16_f32 v152, v162, v163
	v_cvt_pk_bf16_f32 v153, v158, v159
	v_lshl_add_u64 v[154:155], v[154:155], 0, v[200:201]
	s_waitcnt vmcnt(16)
	v_pk_fma_f32 v[22:23], v[22:23], v[126:127], v[250:251]
	v_pk_fma_f32 v[20:21], v[20:21], v[124:125], v[248:249]
	v_pk_fma_f32 v[18:19], v[18:19], v[118:119], v[204:205]
	v_pk_fma_f32 v[16:17], v[16:17], v[116:117], v[202:203]
	global_store_dwordx4 v[156:157], v[28:31], off
	global_store_dwordx4 v[156:157], v[24:27], off offset:16
	global_store_dwordx4 v[154:155], v[150:153], off
	global_store_dwordx4 v[156:157], v[20:23], off offset:512
	global_store_dwordx4 v[156:157], v[16:19], off offset:528
	v_pk_mul_f32 v[152:153], v[226:227], v[22:23]
	v_pk_mul_f32 v[150:151], v[228:229], v[20:21]
	v_pk_mul_f32 v[156:157], v[230:231], v[18:19]
	v_pk_mul_f32 v[158:159], v[232:233], v[16:17]
	v_cvt_pk_bf16_f32 v150, v150, v151
	v_cvt_pk_bf16_f32 v151, v152, v153
	v_cvt_pk_bf16_f32 v152, v158, v159
	v_cvt_pk_bf16_f32 v153, v156, v157
	global_store_dwordx4 v[154:155], v[150:153], off offset:256
	s_waitcnt vmcnt(20)
	v_pk_fma_f32 v[14:15], v[14:15], v[134:135], v[142:143]
	v_pk_fma_f32 v[12:13], v[12:13], v[132:133], v[140:141]
	v_add_u32_e32 v150, 0xb0, v224
	v_subrev_u32_e32 v152, s29, v150
	v_ashrrev_i32_e32 v153, 31, v152
	v_ashrrev_i32_e32 v151, 31, v150
	v_pk_fma_f32 v[10:11], v[10:11], v[130:131], v[138:139]
	v_lshlrev_b64 v[152:153], 13, v[152:153]
	v_lshlrev_b64 v[154:155], 12, v[150:151]
	v_pk_fma_f32 v[8:9], v[8:9], v[128:129], v[136:137]
	v_pk_mul_f32 v[130:131], v[234:235], v[14:15]
	v_pk_mul_f32 v[128:129], v[236:237], v[12:13]
	v_pk_mul_f32 v[132:133], v[238:239], v[10:11]
	s_waitcnt vmcnt(18)
	v_pk_fma_f32 v[6:7], v[6:7], v[126:127], v[122:123]
	v_pk_fma_f32 v[4:5], v[4:5], v[124:125], v[120:121]
	v_pk_fma_f32 v[2:3], v[2:3], v[118:119], v[114:115]
	v_pk_fma_f32 v[0:1], v[0:1], v[116:117], v[112:113]
	v_lshl_add_u64 v[152:153], s[42:43], 0, v[152:153]
	v_pk_mul_f32 v[134:135], v[240:241], v[8:9]
	v_cvt_pk_bf16_f32 v128, v128, v129
	v_cvt_pk_bf16_f32 v129, v130, v131
	v_cvt_pk_bf16_f32 v131, v132, v133
	v_lshl_add_u64 v[132:133], s[20:21], 0, v[154:155]
	v_pk_mul_f32 v[114:115], v[226:227], v[6:7]
	v_pk_mul_f32 v[112:113], v[228:229], v[4:5]
	v_pk_mul_f32 v[116:117], v[230:231], v[2:3]
	v_pk_mul_f32 v[118:119], v[232:233], v[0:1]
	v_lshl_add_u64 v[152:153], v[152:153], 0, v[242:243]
	v_cvt_pk_bf16_f32 v130, v134, v135
	v_lshl_add_u64 v[132:133], v[132:133], 0, v[200:201]
	v_cvt_pk_bf16_f32 v112, v112, v113
	v_cvt_pk_bf16_f32 v113, v114, v115
	v_cvt_pk_bf16_f32 v114, v118, v119
	v_cvt_pk_bf16_f32 v115, v116, v117
	global_store_dwordx4 v[152:153], v[12:15], off
	global_store_dwordx4 v[152:153], v[8:11], off offset:16
	global_store_dwordx4 v[132:133], v[128:131], off
	global_store_dwordx4 v[152:153], v[4:7], off offset:512
	global_store_dwordx4 v[152:153], v[0:3], off offset:528
	global_store_dwordx4 v[132:133], v[112:115], off offset:256
	ds_swizzle_b32 v112, v194 offset:swizzle(SWAP,16)
	s_nop 0
	v_mbcnt_lo_u32_b32 v113, -1, 0
	v_mbcnt_hi_u32_b32 v113, -1, v113
	s_waitcnt lgkmcnt(0)
	v_add_f32_e32 v112, v194, v112
	v_lshlrev_b32_e32 v113, 2, v113
	v_xor_b32_e32 v113, 0x80, v113
	ds_bpermute_b32 v113, v113, v112
	s_and_saveexec_b64 s[40:41], vcc
	s_mov_b32 s74, 0x240000
	s_cbranch_execz .LBB0_1567
	v_lshlrev_b64 v[114:115], 7, v[224:225]
	v_lshl_add_u64 v[114:115], s[24:25], 0, v[114:115]
	v_lshl_add_u64 v[114:115], v[114:115], 0, s[38:39]
	s_mov_b32 s43, s91
	s_lshl_b32 s42, s63, 2
	v_lshl_add_u64 v[114:115], v[114:115], 0, s[42:43]
	s_waitcnt lgkmcnt(0)
	v_add_f32_e32 v112, v112, v113
	global_store_dword v[114:115], v112, off
